# G2 gate epilogue rewritten by hand: 16 gate loads in flight with counted waits, straight-line kind0/kind1 paths
# speedup vs baseline: 1.0171x; 1.0137x over previous
.LBB0_632:
	s_add_i32 s51, s16, 2
	s_add_u32 s4, s2, 0x100
	s_addc_u32 s5, s3, 0
	s_add_i32 s52, 0, 0x10000
	v_add_u32_e32 v144, s52, v196
	ds_read_b128 v[132:135], v144
	ds_read_b128 v[136:139], v144 offset:1024
	ds_read_b128 v[140:143], v144 offset:2048
	ds_read_b128 v[144:147], v144 offset:3072
	s_cmp_eq_u32 s48, s16
	s_cselect_b32 s16, s0, s4
	s_cselect_b32 s17, s1, s5
	s_cselect_b32 s21, s9, s50
	s_cselect_b32 s20, s8, s49
	v_lshl_add_u64 v[168:169], s[2:3], 0, v[176:177]
	s_add_i32 m0, s23, 0xc000
	ds_read_b128 v[148:151], v198
	ds_read_b128 v[152:155], v198 offset:1024
	ds_read_b128 v[156:159], v198 offset:2048
	ds_read_b128 v[160:163], v198 offset:3072
	ds_read_b128 v[180:183], v198 offset:4096
	ds_read_b128 v[184:187], v198 offset:5120
	ds_read_b128 v[188:191], v198 offset:6144
	ds_read_b128 v[192:195], v198 offset:7168
	global_load_lds_dwordx4 v[168:169], off
	v_lshl_add_u64 v[168:169], s[2:3], 0, v[178:179]
	s_add_i32 m0, s23, 0xe000
	s_nop 0
	global_load_lds_dwordx4 v[168:169], off
	s_waitcnt lgkmcnt(8)
	s_barrier
	s_waitcnt lgkmcnt(0)
	s_waitcnt lgkmcnt(0)
	v_mfma_f32_16x16x32_bf16 v[128:131], v[132:135], v[148:151], v[128:131]
	v_mfma_f32_16x16x32_bf16 v[124:127], v[140:143], v[148:151], v[124:127]
	v_mfma_f32_16x16x32_bf16 v[120:123], v[132:135], v[156:159], v[120:123]
	v_mfma_f32_16x16x32_bf16 v[116:119], v[140:143], v[156:159], v[116:119]
	v_mfma_f32_16x16x32_bf16 v[112:115], v[132:135], v[180:183], v[112:115]
	v_mfma_f32_16x16x32_bf16 v[108:111], v[140:143], v[180:183], v[108:111]
	v_mfma_f32_16x16x32_bf16 v[104:107], v[132:135], v[188:191], v[104:107]
	v_mfma_f32_16x16x32_bf16 v[100:103], v[140:143], v[188:191], v[100:103]
	v_mfma_f32_16x16x32_bf16 v[128:131], v[136:139], v[152:155], v[128:131]
	v_mfma_f32_16x16x32_bf16 v[124:127], v[144:147], v[152:155], v[124:127]
	v_mfma_f32_16x16x32_bf16 v[120:123], v[136:139], v[160:163], v[120:123]
	v_mfma_f32_16x16x32_bf16 v[116:119], v[144:147], v[160:163], v[116:119]
	v_mfma_f32_16x16x32_bf16 v[112:115], v[136:139], v[184:187], v[112:115]
	v_mfma_f32_16x16x32_bf16 v[108:111], v[144:147], v[184:187], v[108:111]
	v_mfma_f32_16x16x32_bf16 v[104:107], v[136:139], v[192:195], v[104:107]
	v_mfma_f32_16x16x32_bf16 v[100:103], v[144:147], v[192:195], v[100:103]
	s_barrier
	s_add_i32 s53, 0, 0x14000
	v_add_u32_e32 v168, s53, v196
	s_add_i32 s2, s52, s22
	ds_read_b128 v[200:203], v168
	ds_read_b128 v[204:207], v168 offset:1024
	ds_read_b128 v[208:211], v168 offset:2048
	ds_read_b128 v[220:223], v168 offset:3072
	v_lshl_add_u64 v[168:169], s[20:21], 0, v[2:3]
	s_mov_b32 m0, s2
	v_lshl_add_u64 v[214:215], s[20:21], 0, v[174:175]
	global_load_lds_dwordx4 v[168:169], off
	s_add_i32 m0, s2, 0x2000
	s_nop 0
	global_load_lds_dwordx4 v[214:215], off
	s_barrier
	s_waitcnt lgkmcnt(0)
	s_waitcnt lgkmcnt(0)
	v_mfma_f32_16x16x32_bf16 v[96:99], v[200:203], v[148:151], v[96:99]
	v_mfma_f32_16x16x32_bf16 v[92:95], v[208:211], v[148:151], v[92:95]
	v_mfma_f32_16x16x32_bf16 v[88:91], v[200:203], v[156:159], v[88:91]
	v_mfma_f32_16x16x32_bf16 v[84:87], v[208:211], v[156:159], v[84:87]
	v_mfma_f32_16x16x32_bf16 v[80:83], v[200:203], v[180:183], v[80:83]
	v_mfma_f32_16x16x32_bf16 v[76:79], v[208:211], v[180:183], v[76:79]
	v_mfma_f32_16x16x32_bf16 v[72:75], v[200:203], v[188:191], v[72:75]
	v_mfma_f32_16x16x32_bf16 v[68:71], v[208:211], v[188:191], v[68:71]
	v_mfma_f32_16x16x32_bf16 v[96:99], v[204:207], v[152:155], v[96:99]
	v_mfma_f32_16x16x32_bf16 v[92:95], v[220:223], v[152:155], v[92:95]
	v_mfma_f32_16x16x32_bf16 v[88:91], v[204:207], v[160:163], v[88:91]
	v_mfma_f32_16x16x32_bf16 v[84:87], v[220:223], v[160:163], v[84:87]
	v_mfma_f32_16x16x32_bf16 v[80:83], v[204:207], v[184:187], v[80:83]
	v_mfma_f32_16x16x32_bf16 v[76:79], v[220:223], v[184:187], v[76:79]
	v_mfma_f32_16x16x32_bf16 v[72:75], v[204:207], v[192:195], v[72:75]
	v_mfma_f32_16x16x32_bf16 v[68:71], v[220:223], v[192:195], v[68:71]
	s_mov_b32 m0, s23
	v_lshl_add_u64 v[224:225], s[16:17], 0, v[0:1]
	s_barrier
	ds_read_b128 v[148:151], v198 offset:16384
	ds_read_b128 v[152:155], v198 offset:17408
	ds_read_b128 v[156:159], v198 offset:18432
	ds_read_b128 v[160:163], v198 offset:19456
	ds_read_b128 v[180:183], v198 offset:20480
	ds_read_b128 v[184:187], v198 offset:21504
	ds_read_b128 v[188:191], v198 offset:22528
	ds_read_b128 v[192:195], v198 offset:23552
	global_load_lds_dwordx4 v[224:225], off
	v_lshl_add_u64 v[234:235], s[16:17], 0, v[172:173]
	s_mov_b32 m0, s26
	s_nop 0
	global_load_lds_dwordx4 v[234:235], off
	s_barrier
	s_waitcnt lgkmcnt(0)
	s_waitcnt lgkmcnt(0)
	v_mfma_f32_16x16x32_bf16 v[64:67], v[132:135], v[148:151], v[64:67]
	v_mfma_f32_16x16x32_bf16 v[60:63], v[140:143], v[148:151], v[60:63]
	v_mfma_f32_16x16x32_bf16 v[56:59], v[132:135], v[156:159], v[56:59]
	v_mfma_f32_16x16x32_bf16 v[52:55], v[140:143], v[156:159], v[52:55]
	v_mfma_f32_16x16x32_bf16 v[48:51], v[132:135], v[180:183], v[48:51]
	v_mfma_f32_16x16x32_bf16 v[44:47], v[140:143], v[180:183], v[44:47]
	v_mfma_f32_16x16x32_bf16 v[40:43], v[132:135], v[188:191], v[40:43]
	v_mfma_f32_16x16x32_bf16 v[36:39], v[140:143], v[188:191], v[36:39]
	v_mfma_f32_16x16x32_bf16 v[64:67], v[136:139], v[152:155], v[64:67]
	v_mfma_f32_16x16x32_bf16 v[60:63], v[144:147], v[152:155], v[60:63]
	v_mfma_f32_16x16x32_bf16 v[56:59], v[136:139], v[160:163], v[56:59]
	v_mfma_f32_16x16x32_bf16 v[52:55], v[144:147], v[160:163], v[52:55]
	v_mfma_f32_16x16x32_bf16 v[48:51], v[136:139], v[184:187], v[48:51]
	v_mfma_f32_16x16x32_bf16 v[44:47], v[144:147], v[184:187], v[44:47]
	v_mfma_f32_16x16x32_bf16 v[40:43], v[136:139], v[192:195], v[40:43]
	v_mfma_f32_16x16x32_bf16 v[36:39], v[144:147], v[192:195], v[36:39]
	s_barrier
	s_add_u32 s2, s20, 0x60000
	s_addc_u32 s3, s21, 0
	s_add_i32 s52, s53, s22
	v_lshl_add_u64 v[132:133], s[2:3], 0, v[2:3]
	s_mov_b32 m0, s52
	s_nop 0
	global_load_lds_dwordx4 v[132:133], off
	v_lshl_add_u64 v[132:133], s[2:3], 0, v[174:175]
	s_add_i32 m0, s52, 0x2000
	s_nop 0
	global_load_lds_dwordx4 v[132:133], off
	s_waitcnt vmcnt(6)
	s_barrier
	v_mfma_f32_16x16x32_bf16 v[32:35], v[200:203], v[148:151], v[32:35]
	v_mfma_f32_16x16x32_bf16 v[28:31], v[208:211], v[148:151], v[28:31]
	v_mfma_f32_16x16x32_bf16 v[24:27], v[200:203], v[156:159], v[24:27]
	v_mfma_f32_16x16x32_bf16 v[20:23], v[208:211], v[156:159], v[20:23]
	v_mfma_f32_16x16x32_bf16 v[16:19], v[200:203], v[180:183], v[16:19]
	v_mfma_f32_16x16x32_bf16 v[12:15], v[208:211], v[180:183], v[12:15]
	v_mfma_f32_16x16x32_bf16 v[8:11], v[200:203], v[188:191], v[8:11]
	v_mfma_f32_16x16x32_bf16 v[4:7], v[208:211], v[188:191], v[4:7]
	v_mfma_f32_16x16x32_bf16 v[32:35], v[204:207], v[152:155], v[32:35]
	v_mfma_f32_16x16x32_bf16 v[28:31], v[220:223], v[152:155], v[28:31]
	v_mfma_f32_16x16x32_bf16 v[24:27], v[204:207], v[160:163], v[24:27]
	v_mfma_f32_16x16x32_bf16 v[20:23], v[220:223], v[160:163], v[20:23]
	v_mfma_f32_16x16x32_bf16 v[16:19], v[204:207], v[184:187], v[16:19]
	v_mfma_f32_16x16x32_bf16 v[12:15], v[220:223], v[184:187], v[12:15]
	v_mfma_f32_16x16x32_bf16 v[8:11], v[204:207], v[192:195], v[8:11]
	v_mfma_f32_16x16x32_bf16 v[4:7], v[220:223], v[192:195], v[4:7]
	s_add_i32 s52, 0, 0x18000
	v_add_u32_e32 v144, s52, v196
	s_barrier
	ds_read_b128 v[132:135], v144
	ds_read_b128 v[136:139], v144 offset:1024
	ds_read_b128 v[140:143], v144 offset:2048
	ds_read_b128 v[144:147], v144 offset:3072
	s_add_u32 s2, s16, 0x60000
	s_addc_u32 s3, s17, 0
	s_mov_b32 m0, s27
	v_lshl_add_u64 v[200:201], s[2:3], 0, v[0:1]
	ds_read_b128 v[148:151], v198 offset:32768
	ds_read_b128 v[152:155], v198 offset:33792
	ds_read_b128 v[156:159], v198 offset:34816
	ds_read_b128 v[160:163], v198 offset:35840
	ds_read_b128 v[180:183], v198 offset:36864
	ds_read_b128 v[184:187], v198 offset:37888
	ds_read_b128 v[188:191], v198 offset:38912
	ds_read_b128 v[192:195], v198 offset:39936
	global_load_lds_dwordx4 v[200:201], off
	v_lshl_add_u64 v[200:201], s[2:3], 0, v[172:173]
	s_mov_b32 m0, s30
	s_nop 0
	global_load_lds_dwordx4 v[200:201], off
	s_waitcnt lgkmcnt(8)
	s_barrier
	s_waitcnt lgkmcnt(0)
	s_waitcnt lgkmcnt(0)
	v_mfma_f32_16x16x32_bf16 v[128:131], v[132:135], v[148:151], v[128:131]
	v_mfma_f32_16x16x32_bf16 v[124:127], v[140:143], v[148:151], v[124:127]
	v_mfma_f32_16x16x32_bf16 v[120:123], v[132:135], v[156:159], v[120:123]
	v_mfma_f32_16x16x32_bf16 v[116:119], v[140:143], v[156:159], v[116:119]
	v_mfma_f32_16x16x32_bf16 v[112:115], v[132:135], v[180:183], v[112:115]
	v_mfma_f32_16x16x32_bf16 v[108:111], v[140:143], v[180:183], v[108:111]
	v_mfma_f32_16x16x32_bf16 v[104:107], v[132:135], v[188:191], v[104:107]
	v_mfma_f32_16x16x32_bf16 v[100:103], v[140:143], v[188:191], v[100:103]
	v_mfma_f32_16x16x32_bf16 v[128:131], v[136:139], v[152:155], v[128:131]
	v_mfma_f32_16x16x32_bf16 v[124:127], v[144:147], v[152:155], v[124:127]
	v_mfma_f32_16x16x32_bf16 v[120:123], v[136:139], v[160:163], v[120:123]
	v_mfma_f32_16x16x32_bf16 v[116:119], v[144:147], v[160:163], v[116:119]
	v_mfma_f32_16x16x32_bf16 v[112:115], v[136:139], v[184:187], v[112:115]
	v_mfma_f32_16x16x32_bf16 v[108:111], v[144:147], v[184:187], v[108:111]
	v_mfma_f32_16x16x32_bf16 v[104:107], v[136:139], v[192:195], v[104:107]
	v_mfma_f32_16x16x32_bf16 v[100:103], v[144:147], v[192:195], v[100:103]
	s_barrier
	s_add_i32 s16, 0, 0x1c000
	s_add_i32 s2, s52, s22
	v_add_u32_e32 v199, s16, v196
	v_lshl_add_u64 v[168:169], v[168:169], 0, s[28:29]
	s_mov_b32 m0, s2
	ds_read_b128 v[200:203], v199
	ds_read_b128 v[204:207], v199 offset:1024
	ds_read_b128 v[208:211], v199 offset:2048
	ds_read_b128 v[220:223], v199 offset:3072
	global_load_lds_dwordx4 v[168:169], off
	v_lshl_add_u64 v[168:169], v[214:215], 0, s[28:29]
	s_add_i32 m0, s2, 0x2000
	s_nop 0
	global_load_lds_dwordx4 v[168:169], off
	s_barrier
	s_waitcnt lgkmcnt(0)
	s_waitcnt lgkmcnt(0)
	v_mfma_f32_16x16x32_bf16 v[96:99], v[200:203], v[148:151], v[96:99]
	v_mfma_f32_16x16x32_bf16 v[92:95], v[208:211], v[148:151], v[92:95]
	v_mfma_f32_16x16x32_bf16 v[88:91], v[200:203], v[156:159], v[88:91]
	v_mfma_f32_16x16x32_bf16 v[84:87], v[208:211], v[156:159], v[84:87]
	v_mfma_f32_16x16x32_bf16 v[80:83], v[200:203], v[180:183], v[80:83]
	v_mfma_f32_16x16x32_bf16 v[76:79], v[208:211], v[180:183], v[76:79]
	v_mfma_f32_16x16x32_bf16 v[72:75], v[200:203], v[188:191], v[72:75]
	v_mfma_f32_16x16x32_bf16 v[68:71], v[208:211], v[188:191], v[68:71]
	v_mfma_f32_16x16x32_bf16 v[96:99], v[204:207], v[152:155], v[96:99]
	v_mfma_f32_16x16x32_bf16 v[92:95], v[220:223], v[152:155], v[92:95]
	v_mfma_f32_16x16x32_bf16 v[88:91], v[204:207], v[160:163], v[88:91]
	v_mfma_f32_16x16x32_bf16 v[84:87], v[220:223], v[160:163], v[84:87]
	v_mfma_f32_16x16x32_bf16 v[80:83], v[204:207], v[184:187], v[80:83]
	v_mfma_f32_16x16x32_bf16 v[76:79], v[220:223], v[184:187], v[76:79]
	v_mfma_f32_16x16x32_bf16 v[72:75], v[204:207], v[192:195], v[72:75]
	v_mfma_f32_16x16x32_bf16 v[68:71], v[220:223], v[192:195], v[68:71]
	s_mov_b32 m0, s31
	v_lshl_add_u64 v[168:169], v[224:225], 0, s[28:29]
	s_barrier
	ds_read_b128 v[148:151], v198 offset:49152
	ds_read_b128 v[152:155], v198 offset:50176
	ds_read_b128 v[156:159], v198 offset:51200
	ds_read_b128 v[160:163], v198 offset:52224
	ds_read_b128 v[180:183], v198 offset:53248
	ds_read_b128 v[184:187], v198 offset:54272
	ds_read_b128 v[188:191], v198 offset:55296
	ds_read_b128 v[192:195], v198 offset:56320
	global_load_lds_dwordx4 v[168:169], off
	v_lshl_add_u64 v[168:169], v[234:235], 0, s[28:29]
	s_mov_b32 m0, s42
	s_nop 0
	global_load_lds_dwordx4 v[168:169], off
	s_barrier
	s_waitcnt lgkmcnt(0)
	s_waitcnt lgkmcnt(0)
	v_mfma_f32_16x16x32_bf16 v[64:67], v[132:135], v[148:151], v[64:67]
	v_mfma_f32_16x16x32_bf16 v[60:63], v[140:143], v[148:151], v[60:63]
	v_mfma_f32_16x16x32_bf16 v[56:59], v[132:135], v[156:159], v[56:59]
	v_mfma_f32_16x16x32_bf16 v[52:55], v[140:143], v[156:159], v[52:55]
	v_mfma_f32_16x16x32_bf16 v[48:51], v[132:135], v[180:183], v[48:51]
	v_mfma_f32_16x16x32_bf16 v[44:47], v[140:143], v[180:183], v[44:47]
	v_mfma_f32_16x16x32_bf16 v[40:43], v[132:135], v[188:191], v[40:43]
	v_mfma_f32_16x16x32_bf16 v[36:39], v[140:143], v[188:191], v[36:39]
	v_mfma_f32_16x16x32_bf16 v[64:67], v[136:139], v[152:155], v[64:67]
	v_mfma_f32_16x16x32_bf16 v[60:63], v[144:147], v[152:155], v[60:63]
	v_mfma_f32_16x16x32_bf16 v[56:59], v[136:139], v[160:163], v[56:59]
	v_mfma_f32_16x16x32_bf16 v[52:55], v[144:147], v[160:163], v[52:55]
	v_mfma_f32_16x16x32_bf16 v[48:51], v[136:139], v[184:187], v[48:51]
	v_mfma_f32_16x16x32_bf16 v[44:47], v[144:147], v[184:187], v[44:47]
	v_mfma_f32_16x16x32_bf16 v[40:43], v[136:139], v[192:195], v[40:43]
	v_mfma_f32_16x16x32_bf16 v[36:39], v[144:147], v[192:195], v[36:39]
	s_barrier
	s_add_u32 s2, s20, 0x60080
	s_addc_u32 s3, s21, 0
	s_add_i32 s16, s16, s22
	v_lshl_add_u64 v[132:133], s[2:3], 0, v[2:3]
	s_mov_b32 m0, s16
	s_nop 0
	global_load_lds_dwordx4 v[132:133], off
	v_lshl_add_u64 v[132:133], s[2:3], 0, v[174:175]
	s_add_i32 m0, s16, 0x2000
	s_nop 0
	global_load_lds_dwordx4 v[132:133], off
	s_waitcnt vmcnt(6)
	s_barrier
	v_mfma_f32_16x16x32_bf16 v[32:35], v[200:203], v[148:151], v[32:35]
	v_mfma_f32_16x16x32_bf16 v[28:31], v[208:211], v[148:151], v[28:31]
	v_mfma_f32_16x16x32_bf16 v[24:27], v[200:203], v[156:159], v[24:27]
	v_mfma_f32_16x16x32_bf16 v[20:23], v[208:211], v[156:159], v[20:23]
	v_mfma_f32_16x16x32_bf16 v[16:19], v[200:203], v[180:183], v[16:19]
	v_mfma_f32_16x16x32_bf16 v[12:15], v[208:211], v[180:183], v[12:15]
	v_mfma_f32_16x16x32_bf16 v[8:11], v[200:203], v[188:191], v[8:11]
	v_mfma_f32_16x16x32_bf16 v[4:7], v[208:211], v[188:191], v[4:7]
	v_mfma_f32_16x16x32_bf16 v[32:35], v[204:207], v[152:155], v[32:35]
	v_mfma_f32_16x16x32_bf16 v[28:31], v[220:223], v[152:155], v[28:31]
	v_mfma_f32_16x16x32_bf16 v[24:27], v[204:207], v[160:163], v[24:27]
	v_mfma_f32_16x16x32_bf16 v[20:23], v[220:223], v[160:163], v[20:23]
	v_mfma_f32_16x16x32_bf16 v[16:19], v[204:207], v[184:187], v[16:19]
	v_mfma_f32_16x16x32_bf16 v[12:15], v[220:223], v[184:187], v[12:15]
	v_mfma_f32_16x16x32_bf16 v[8:11], v[204:207], v[192:195], v[8:11]
	v_mfma_f32_16x16x32_bf16 v[4:7], v[220:223], v[192:195], v[4:7]
	s_add_u32 s49, s49, 0x100
	s_addc_u32 s50, s50, 0
	s_cmp_ge_i32 s51, s40
	s_mov_b64 s[2:3], s[4:5]
	s_mov_b32 s16, s51
	s_barrier
	s_cbranch_scc0 .LBB0_632
	v_lshl_add_u32 v199, s41, 8, v170
	v_lshl_or_b32 v168, s37, 8, v197
	v_lshlrev_b32_e32 v199, 11, v199
	v_lshl_add_u32 v199, v168, 1, v199
	v_readlane_b32 s2, v252, 60
	v_readlane_b32 s3, v252, 61
	v_readlane_b32 s16, v252, 58
	v_readlane_b32 s17, v252, 59
	s_mov_b64 s[48:49], 0x5201400
	s_cmp_lg_u32 s36, 0
	s_cbranch_scc1 .Lg2e_k1
	s_add_u32 s4, s2, 0x0
	s_addc_u32 s5, s3, 0
	s_add_u32 s40, s16, 0x0
	s_addc_u32 s41, s17, 0
	global_load_dwordx4 v[132:135], v199, s[4:5]
	global_load_dwordx4 v[136:139], v199, s[40:41]
	s_add_u32 s4, s2, 0x8000
	s_addc_u32 s5, s3, 0
	s_add_u32 s40, s16, 0x8000
	s_addc_u32 s41, s17, 0
	global_load_dwordx4 v[140:143], v199, s[4:5]
	global_load_dwordx4 v[144:147], v199, s[40:41]
	s_add_u32 s4, s2, 0x10000
	s_addc_u32 s5, s3, 0
	s_add_u32 s40, s16, 0x10000
	s_addc_u32 s41, s17, 0
	global_load_dwordx4 v[148:151], v199, s[4:5]
	global_load_dwordx4 v[152:155], v199, s[40:41]
	s_add_u32 s4, s2, 0x18000
	s_addc_u32 s5, s3, 0
	s_add_u32 s40, s16, 0x18000
	s_addc_u32 s41, s17, 0
	global_load_dwordx4 v[156:159], v199, s[4:5]
	global_load_dwordx4 v[160:163], v199, s[40:41]
	s_add_u32 s4, s2, 0x40000
	s_addc_u32 s5, s3, 0
	s_add_u32 s40, s16, 0x40000
	s_addc_u32 s41, s17, 0
	global_load_dwordx4 v[180:183], v199, s[4:5]
	global_load_dwordx4 v[184:187], v199, s[40:41]
	s_add_u32 s4, s2, 0x48000
	s_addc_u32 s5, s3, 0
	s_add_u32 s40, s16, 0x48000
	s_addc_u32 s41, s17, 0
	global_load_dwordx4 v[188:191], v199, s[4:5]
	global_load_dwordx4 v[192:195], v199, s[40:41]
	s_add_u32 s4, s2, 0x50000
	s_addc_u32 s5, s3, 0
	s_add_u32 s40, s16, 0x50000
	s_addc_u32 s41, s17, 0
	global_load_dwordx4 v[200:203], v199, s[4:5]
	global_load_dwordx4 v[204:207], v199, s[40:41]
	s_add_u32 s4, s2, 0x58000
	s_addc_u32 s5, s3, 0
	s_add_u32 s40, s16, 0x58000
	s_addc_u32 s41, s17, 0
	global_load_dwordx4 v[208:211], v199, s[4:5]
	global_load_dwordx4 v[220:223], v199, s[40:41]
	s_waitcnt vmcnt(14)
	v_lshlrev_b32_e32 v168, 16, v132
	v_and_b32_e32 v132, 0xffff0000, v132
	v_lshlrev_b32_e32 v169, 16, v136
	v_and_b32_e32 v136, 0xffff0000, v136
	v_lshlrev_b32_e32 v214, 16, v133
	v_and_b32_e32 v133, 0xffff0000, v133
	v_lshlrev_b32_e32 v215, 16, v137
	v_and_b32_e32 v137, 0xffff0000, v137
	v_lshlrev_b32_e32 v224, 16, v134
	v_and_b32_e32 v134, 0xffff0000, v134
	v_lshlrev_b32_e32 v225, 16, v138
	v_and_b32_e32 v138, 0xffff0000, v138
	v_lshlrev_b32_e32 v234, 16, v135
	v_and_b32_e32 v135, 0xffff0000, v135
	v_lshlrev_b32_e32 v235, 16, v139
	v_and_b32_e32 v139, 0xffff0000, v139
	v_max_f32_e32 v168, 0xda24260, v168
	v_max_f32_e32 v132, 0xda24260, v132
	v_max_f32_e32 v214, 0xda24260, v214
	v_max_f32_e32 v133, 0xda24260, v133
	v_max_f32_e32 v224, 0xda24260, v224
	v_max_f32_e32 v134, 0xda24260, v134
	v_max_f32_e32 v234, 0xda24260, v234
	v_max_f32_e32 v135, 0xda24260, v135
	v_rcp_f32_e32 v168, v168
	v_rcp_f32_e32 v132, v132
	v_rcp_f32_e32 v214, v214
	v_rcp_f32_e32 v133, v133
	v_rcp_f32_e32 v224, v224
	v_rcp_f32_e32 v134, v134
	v_rcp_f32_e32 v234, v234
	v_rcp_f32_e32 v135, v135
	v_mul_f32_e32 v168, v168, v169
	v_mul_f32_e32 v132, v132, v136
	v_mul_f32_e32 v214, v214, v215
	v_mul_f32_e32 v133, v133, v137
	v_mul_f32_e32 v224, v224, v225
	v_mul_f32_e32 v134, v134, v138
	v_mul_f32_e32 v234, v234, v235
	v_mul_f32_e32 v135, v135, v139
	v_mul_f32_e32 v128, v128, v168
	v_mul_f32_e32 v129, v129, v132
	v_mul_f32_e32 v130, v130, v214
	v_mul_f32_e32 v131, v131, v133
	v_mul_f32_e32 v124, v124, v224
	v_mul_f32_e32 v125, v125, v134
	v_mul_f32_e32 v126, v126, v234
	v_mul_f32_e32 v127, v127, v135
	s_add_u32 s4, s2, 0x0
	s_addc_u32 s5, s3, 0
	s_add_u32 s40, s16, 0x0
	s_addc_u32 s41, s17, 0
	global_load_dwordx4 v[132:135], v199, s[4:5] offset:256
	global_load_dwordx4 v[136:139], v199, s[40:41] offset:256
	s_waitcnt vmcnt(14)
	v_lshlrev_b32_e32 v168, 16, v140
	v_and_b32_e32 v140, 0xffff0000, v140
	v_lshlrev_b32_e32 v169, 16, v144
	v_and_b32_e32 v144, 0xffff0000, v144
	v_lshlrev_b32_e32 v214, 16, v141
	v_and_b32_e32 v141, 0xffff0000, v141
	v_lshlrev_b32_e32 v215, 16, v145
	v_and_b32_e32 v145, 0xffff0000, v145
	v_lshlrev_b32_e32 v224, 16, v142
	v_and_b32_e32 v142, 0xffff0000, v142
	v_lshlrev_b32_e32 v225, 16, v146
	v_and_b32_e32 v146, 0xffff0000, v146
	v_lshlrev_b32_e32 v234, 16, v143
	v_and_b32_e32 v143, 0xffff0000, v143
	v_lshlrev_b32_e32 v235, 16, v147
	v_and_b32_e32 v147, 0xffff0000, v147
	v_max_f32_e32 v168, 0xda24260, v168
	v_max_f32_e32 v140, 0xda24260, v140
	v_max_f32_e32 v214, 0xda24260, v214
	v_max_f32_e32 v141, 0xda24260, v141
	v_max_f32_e32 v224, 0xda24260, v224
	v_max_f32_e32 v142, 0xda24260, v142
	v_max_f32_e32 v234, 0xda24260, v234
	v_max_f32_e32 v143, 0xda24260, v143
	v_rcp_f32_e32 v168, v168
	v_rcp_f32_e32 v140, v140
	v_rcp_f32_e32 v214, v214
	v_rcp_f32_e32 v141, v141
	v_rcp_f32_e32 v224, v224
	v_rcp_f32_e32 v142, v142
	v_rcp_f32_e32 v234, v234
	v_rcp_f32_e32 v143, v143
	v_mul_f32_e32 v168, v168, v169
	v_mul_f32_e32 v140, v140, v144
	v_mul_f32_e32 v214, v214, v215
	v_mul_f32_e32 v141, v141, v145
	v_mul_f32_e32 v224, v224, v225
	v_mul_f32_e32 v142, v142, v146
	v_mul_f32_e32 v234, v234, v235
	v_mul_f32_e32 v143, v143, v147
	v_mul_f32_e32 v120, v120, v168
	v_mul_f32_e32 v121, v121, v140
	v_mul_f32_e32 v122, v122, v214
	v_mul_f32_e32 v123, v123, v141
	v_mul_f32_e32 v116, v116, v224
	v_mul_f32_e32 v117, v117, v142
	v_mul_f32_e32 v118, v118, v234
	v_mul_f32_e32 v119, v119, v143
	s_add_u32 s4, s2, 0x8000
	s_addc_u32 s5, s3, 0
	s_add_u32 s40, s16, 0x8000
	s_addc_u32 s41, s17, 0
	global_load_dwordx4 v[140:143], v199, s[4:5] offset:256
	global_load_dwordx4 v[144:147], v199, s[40:41] offset:256
	s_waitcnt vmcnt(14)
	v_lshlrev_b32_e32 v168, 16, v148
	v_and_b32_e32 v148, 0xffff0000, v148
	v_lshlrev_b32_e32 v169, 16, v152
	v_and_b32_e32 v152, 0xffff0000, v152
	v_lshlrev_b32_e32 v214, 16, v149
	v_and_b32_e32 v149, 0xffff0000, v149
	v_lshlrev_b32_e32 v215, 16, v153
	v_and_b32_e32 v153, 0xffff0000, v153
	v_lshlrev_b32_e32 v224, 16, v150
	v_and_b32_e32 v150, 0xffff0000, v150
	v_lshlrev_b32_e32 v225, 16, v154
	v_and_b32_e32 v154, 0xffff0000, v154
	v_lshlrev_b32_e32 v234, 16, v151
	v_and_b32_e32 v151, 0xffff0000, v151
	v_lshlrev_b32_e32 v235, 16, v155
	v_and_b32_e32 v155, 0xffff0000, v155
	v_max_f32_e32 v168, 0xda24260, v168
	v_max_f32_e32 v148, 0xda24260, v148
	v_max_f32_e32 v214, 0xda24260, v214
	v_max_f32_e32 v149, 0xda24260, v149
	v_max_f32_e32 v224, 0xda24260, v224
	v_max_f32_e32 v150, 0xda24260, v150
	v_max_f32_e32 v234, 0xda24260, v234
	v_max_f32_e32 v151, 0xda24260, v151
	v_rcp_f32_e32 v168, v168
	v_rcp_f32_e32 v148, v148
	v_rcp_f32_e32 v214, v214
	v_rcp_f32_e32 v149, v149
	v_rcp_f32_e32 v224, v224
	v_rcp_f32_e32 v150, v150
	v_rcp_f32_e32 v234, v234
	v_rcp_f32_e32 v151, v151
	v_mul_f32_e32 v168, v168, v169
	v_mul_f32_e32 v148, v148, v152
	v_mul_f32_e32 v214, v214, v215
	v_mul_f32_e32 v149, v149, v153
	v_mul_f32_e32 v224, v224, v225
	v_mul_f32_e32 v150, v150, v154
	v_mul_f32_e32 v234, v234, v235
	v_mul_f32_e32 v151, v151, v155
	v_mul_f32_e32 v112, v112, v168
	v_mul_f32_e32 v113, v113, v148
	v_mul_f32_e32 v114, v114, v214
	v_mul_f32_e32 v115, v115, v149
	v_mul_f32_e32 v108, v108, v224
	v_mul_f32_e32 v109, v109, v150
	v_mul_f32_e32 v110, v110, v234
	v_mul_f32_e32 v111, v111, v151
	s_add_u32 s4, s2, 0x10000
	s_addc_u32 s5, s3, 0
	s_add_u32 s40, s16, 0x10000
	s_addc_u32 s41, s17, 0
	global_load_dwordx4 v[148:151], v199, s[4:5] offset:256
	global_load_dwordx4 v[152:155], v199, s[40:41] offset:256
	s_waitcnt vmcnt(14)
	v_lshlrev_b32_e32 v168, 16, v156
	v_and_b32_e32 v156, 0xffff0000, v156
	v_lshlrev_b32_e32 v169, 16, v160
	v_and_b32_e32 v160, 0xffff0000, v160
	v_lshlrev_b32_e32 v214, 16, v157
	v_and_b32_e32 v157, 0xffff0000, v157
	v_lshlrev_b32_e32 v215, 16, v161
	v_and_b32_e32 v161, 0xffff0000, v161
	v_lshlrev_b32_e32 v224, 16, v158
	v_and_b32_e32 v158, 0xffff0000, v158
	v_lshlrev_b32_e32 v225, 16, v162
	v_and_b32_e32 v162, 0xffff0000, v162
	v_lshlrev_b32_e32 v234, 16, v159
	v_and_b32_e32 v159, 0xffff0000, v159
	v_lshlrev_b32_e32 v235, 16, v163
	v_and_b32_e32 v163, 0xffff0000, v163
	v_max_f32_e32 v168, 0xda24260, v168
	v_max_f32_e32 v156, 0xda24260, v156
	v_max_f32_e32 v214, 0xda24260, v214
	v_max_f32_e32 v157, 0xda24260, v157
	v_max_f32_e32 v224, 0xda24260, v224
	v_max_f32_e32 v158, 0xda24260, v158
	v_max_f32_e32 v234, 0xda24260, v234
	v_max_f32_e32 v159, 0xda24260, v159
	v_rcp_f32_e32 v168, v168
	v_rcp_f32_e32 v156, v156
	v_rcp_f32_e32 v214, v214
	v_rcp_f32_e32 v157, v157
	v_rcp_f32_e32 v224, v224
	v_rcp_f32_e32 v158, v158
	v_rcp_f32_e32 v234, v234
	v_rcp_f32_e32 v159, v159
	v_mul_f32_e32 v168, v168, v169
	v_mul_f32_e32 v156, v156, v160
	v_mul_f32_e32 v214, v214, v215
	v_mul_f32_e32 v157, v157, v161
	v_mul_f32_e32 v224, v224, v225
	v_mul_f32_e32 v158, v158, v162
	v_mul_f32_e32 v234, v234, v235
	v_mul_f32_e32 v159, v159, v163
	v_mul_f32_e32 v104, v104, v168
	v_mul_f32_e32 v105, v105, v156
	v_mul_f32_e32 v106, v106, v214
	v_mul_f32_e32 v107, v107, v157
	v_mul_f32_e32 v100, v100, v224
	v_mul_f32_e32 v101, v101, v158
	v_mul_f32_e32 v102, v102, v234
	v_mul_f32_e32 v103, v103, v159
	s_add_u32 s4, s2, 0x18000
	s_addc_u32 s5, s3, 0
	s_add_u32 s40, s16, 0x18000
	s_addc_u32 s41, s17, 0
	global_load_dwordx4 v[156:159], v199, s[4:5] offset:256
	global_load_dwordx4 v[160:163], v199, s[40:41] offset:256
	s_waitcnt vmcnt(14)
	v_lshlrev_b32_e32 v168, 16, v180
	v_and_b32_e32 v180, 0xffff0000, v180
	v_lshlrev_b32_e32 v169, 16, v184
	v_and_b32_e32 v184, 0xffff0000, v184
	v_lshlrev_b32_e32 v214, 16, v181
	v_and_b32_e32 v181, 0xffff0000, v181
	v_lshlrev_b32_e32 v215, 16, v185
	v_and_b32_e32 v185, 0xffff0000, v185
	v_lshlrev_b32_e32 v224, 16, v182
	v_and_b32_e32 v182, 0xffff0000, v182
	v_lshlrev_b32_e32 v225, 16, v186
	v_and_b32_e32 v186, 0xffff0000, v186
	v_lshlrev_b32_e32 v234, 16, v183
	v_and_b32_e32 v183, 0xffff0000, v183
	v_lshlrev_b32_e32 v235, 16, v187
	v_and_b32_e32 v187, 0xffff0000, v187
	v_max_f32_e32 v168, 0xda24260, v168
	v_max_f32_e32 v180, 0xda24260, v180
	v_max_f32_e32 v214, 0xda24260, v214
	v_max_f32_e32 v181, 0xda24260, v181
	v_max_f32_e32 v224, 0xda24260, v224
	v_max_f32_e32 v182, 0xda24260, v182
	v_max_f32_e32 v234, 0xda24260, v234
	v_max_f32_e32 v183, 0xda24260, v183
	v_rcp_f32_e32 v168, v168
	v_rcp_f32_e32 v180, v180
	v_rcp_f32_e32 v214, v214
	v_rcp_f32_e32 v181, v181
	v_rcp_f32_e32 v224, v224
	v_rcp_f32_e32 v182, v182
	v_rcp_f32_e32 v234, v234
	v_rcp_f32_e32 v183, v183
	v_mul_f32_e32 v168, v168, v169
	v_mul_f32_e32 v180, v180, v184
	v_mul_f32_e32 v214, v214, v215
	v_mul_f32_e32 v181, v181, v185
	v_mul_f32_e32 v224, v224, v225
	v_mul_f32_e32 v182, v182, v186
	v_mul_f32_e32 v234, v234, v235
	v_mul_f32_e32 v183, v183, v187
	v_mul_f32_e32 v64, v64, v168
	v_mul_f32_e32 v65, v65, v180
	v_mul_f32_e32 v66, v66, v214
	v_mul_f32_e32 v67, v67, v181
	v_mul_f32_e32 v60, v60, v224
	v_mul_f32_e32 v61, v61, v182
	v_mul_f32_e32 v62, v62, v234
	v_mul_f32_e32 v63, v63, v183
	s_add_u32 s4, s2, 0x40000
	s_addc_u32 s5, s3, 0
	s_add_u32 s40, s16, 0x40000
	s_addc_u32 s41, s17, 0
	global_load_dwordx4 v[180:183], v199, s[4:5] offset:256
	global_load_dwordx4 v[184:187], v199, s[40:41] offset:256
	s_waitcnt vmcnt(14)
	v_lshlrev_b32_e32 v168, 16, v188
	v_and_b32_e32 v188, 0xffff0000, v188
	v_lshlrev_b32_e32 v169, 16, v192
	v_and_b32_e32 v192, 0xffff0000, v192
	v_lshlrev_b32_e32 v214, 16, v189
	v_and_b32_e32 v189, 0xffff0000, v189
	v_lshlrev_b32_e32 v215, 16, v193
	v_and_b32_e32 v193, 0xffff0000, v193
	v_lshlrev_b32_e32 v224, 16, v190
	v_and_b32_e32 v190, 0xffff0000, v190
	v_lshlrev_b32_e32 v225, 16, v194
	v_and_b32_e32 v194, 0xffff0000, v194
	v_lshlrev_b32_e32 v234, 16, v191
	v_and_b32_e32 v191, 0xffff0000, v191
	v_lshlrev_b32_e32 v235, 16, v195
	v_and_b32_e32 v195, 0xffff0000, v195
	v_max_f32_e32 v168, 0xda24260, v168
	v_max_f32_e32 v188, 0xda24260, v188
	v_max_f32_e32 v214, 0xda24260, v214
	v_max_f32_e32 v189, 0xda24260, v189
	v_max_f32_e32 v224, 0xda24260, v224
	v_max_f32_e32 v190, 0xda24260, v190
	v_max_f32_e32 v234, 0xda24260, v234
	v_max_f32_e32 v191, 0xda24260, v191
	v_rcp_f32_e32 v168, v168
	v_rcp_f32_e32 v188, v188
	v_rcp_f32_e32 v214, v214
	v_rcp_f32_e32 v189, v189
	v_rcp_f32_e32 v224, v224
	v_rcp_f32_e32 v190, v190
	v_rcp_f32_e32 v234, v234
	v_rcp_f32_e32 v191, v191
	v_mul_f32_e32 v168, v168, v169
	v_mul_f32_e32 v188, v188, v192
	v_mul_f32_e32 v214, v214, v215
	v_mul_f32_e32 v189, v189, v193
	v_mul_f32_e32 v224, v224, v225
	v_mul_f32_e32 v190, v190, v194
	v_mul_f32_e32 v234, v234, v235
	v_mul_f32_e32 v191, v191, v195
	v_mul_f32_e32 v56, v56, v168
	v_mul_f32_e32 v57, v57, v188
	v_mul_f32_e32 v58, v58, v214
	v_mul_f32_e32 v59, v59, v189
	v_mul_f32_e32 v52, v52, v224
	v_mul_f32_e32 v53, v53, v190
	v_mul_f32_e32 v54, v54, v234
	v_mul_f32_e32 v55, v55, v191
	s_add_u32 s4, s2, 0x48000
	s_addc_u32 s5, s3, 0
	s_add_u32 s40, s16, 0x48000
	s_addc_u32 s41, s17, 0
	global_load_dwordx4 v[188:191], v199, s[4:5] offset:256
	global_load_dwordx4 v[192:195], v199, s[40:41] offset:256
	s_waitcnt vmcnt(14)
	v_lshlrev_b32_e32 v168, 16, v200
	v_and_b32_e32 v200, 0xffff0000, v200
	v_lshlrev_b32_e32 v169, 16, v204
	v_and_b32_e32 v204, 0xffff0000, v204
	v_lshlrev_b32_e32 v214, 16, v201
	v_and_b32_e32 v201, 0xffff0000, v201
	v_lshlrev_b32_e32 v215, 16, v205
	v_and_b32_e32 v205, 0xffff0000, v205
	v_lshlrev_b32_e32 v224, 16, v202
	v_and_b32_e32 v202, 0xffff0000, v202
	v_lshlrev_b32_e32 v225, 16, v206
	v_and_b32_e32 v206, 0xffff0000, v206
	v_lshlrev_b32_e32 v234, 16, v203
	v_and_b32_e32 v203, 0xffff0000, v203
	v_lshlrev_b32_e32 v235, 16, v207
	v_and_b32_e32 v207, 0xffff0000, v207
	v_max_f32_e32 v168, 0xda24260, v168
	v_max_f32_e32 v200, 0xda24260, v200
	v_max_f32_e32 v214, 0xda24260, v214
	v_max_f32_e32 v201, 0xda24260, v201
	v_max_f32_e32 v224, 0xda24260, v224
	v_max_f32_e32 v202, 0xda24260, v202
	v_max_f32_e32 v234, 0xda24260, v234
	v_max_f32_e32 v203, 0xda24260, v203
	v_rcp_f32_e32 v168, v168
	v_rcp_f32_e32 v200, v200
	v_rcp_f32_e32 v214, v214
	v_rcp_f32_e32 v201, v201
	v_rcp_f32_e32 v224, v224
	v_rcp_f32_e32 v202, v202
	v_rcp_f32_e32 v234, v234
	v_rcp_f32_e32 v203, v203
	v_mul_f32_e32 v168, v168, v169
	v_mul_f32_e32 v200, v200, v204
	v_mul_f32_e32 v214, v214, v215
	v_mul_f32_e32 v201, v201, v205
	v_mul_f32_e32 v224, v224, v225
	v_mul_f32_e32 v202, v202, v206
	v_mul_f32_e32 v234, v234, v235
	v_mul_f32_e32 v203, v203, v207
	v_mul_f32_e32 v48, v48, v168
	v_mul_f32_e32 v49, v49, v200
	v_mul_f32_e32 v50, v50, v214
	v_mul_f32_e32 v51, v51, v201
	v_mul_f32_e32 v44, v44, v224
	v_mul_f32_e32 v45, v45, v202
	v_mul_f32_e32 v46, v46, v234
	v_mul_f32_e32 v47, v47, v203
	s_add_u32 s4, s2, 0x50000
	s_addc_u32 s5, s3, 0
	s_add_u32 s40, s16, 0x50000
	s_addc_u32 s41, s17, 0
	global_load_dwordx4 v[200:203], v199, s[4:5] offset:256
	global_load_dwordx4 v[204:207], v199, s[40:41] offset:256
	s_waitcnt vmcnt(14)
	v_lshlrev_b32_e32 v168, 16, v208
	v_and_b32_e32 v208, 0xffff0000, v208
	v_lshlrev_b32_e32 v169, 16, v220
	v_and_b32_e32 v220, 0xffff0000, v220
	v_lshlrev_b32_e32 v214, 16, v209
	v_and_b32_e32 v209, 0xffff0000, v209
	v_lshlrev_b32_e32 v215, 16, v221
	v_and_b32_e32 v221, 0xffff0000, v221
	v_lshlrev_b32_e32 v224, 16, v210
	v_and_b32_e32 v210, 0xffff0000, v210
	v_lshlrev_b32_e32 v225, 16, v222
	v_and_b32_e32 v222, 0xffff0000, v222
	v_lshlrev_b32_e32 v234, 16, v211
	v_and_b32_e32 v211, 0xffff0000, v211
	v_lshlrev_b32_e32 v235, 16, v223
	v_and_b32_e32 v223, 0xffff0000, v223
	v_max_f32_e32 v168, 0xda24260, v168
	v_max_f32_e32 v208, 0xda24260, v208
	v_max_f32_e32 v214, 0xda24260, v214
	v_max_f32_e32 v209, 0xda24260, v209
	v_max_f32_e32 v224, 0xda24260, v224
	v_max_f32_e32 v210, 0xda24260, v210
	v_max_f32_e32 v234, 0xda24260, v234
	v_max_f32_e32 v211, 0xda24260, v211
	v_rcp_f32_e32 v168, v168
	v_rcp_f32_e32 v208, v208
	v_rcp_f32_e32 v214, v214
	v_rcp_f32_e32 v209, v209
	v_rcp_f32_e32 v224, v224
	v_rcp_f32_e32 v210, v210
	v_rcp_f32_e32 v234, v234
	v_rcp_f32_e32 v211, v211
	v_mul_f32_e32 v168, v168, v169
	v_mul_f32_e32 v208, v208, v220
	v_mul_f32_e32 v214, v214, v215
	v_mul_f32_e32 v209, v209, v221
	v_mul_f32_e32 v224, v224, v225
	v_mul_f32_e32 v210, v210, v222
	v_mul_f32_e32 v234, v234, v235
	v_mul_f32_e32 v211, v211, v223
	v_mul_f32_e32 v40, v40, v168
	v_mul_f32_e32 v41, v41, v208
	v_mul_f32_e32 v42, v42, v214
	v_mul_f32_e32 v43, v43, v209
	v_mul_f32_e32 v36, v36, v224
	v_mul_f32_e32 v37, v37, v210
	v_mul_f32_e32 v38, v38, v234
	v_mul_f32_e32 v39, v39, v211
	s_add_u32 s4, s2, 0x58000
	s_addc_u32 s5, s3, 0
	s_add_u32 s40, s16, 0x58000
	s_addc_u32 s41, s17, 0
	global_load_dwordx4 v[208:211], v199, s[4:5] offset:256
	global_load_dwordx4 v[220:223], v199, s[40:41] offset:256
	s_waitcnt vmcnt(14)
	v_lshlrev_b32_e32 v168, 16, v132
	v_and_b32_e32 v132, 0xffff0000, v132
	v_lshlrev_b32_e32 v169, 16, v136
	v_and_b32_e32 v136, 0xffff0000, v136
	v_lshlrev_b32_e32 v214, 16, v133
	v_and_b32_e32 v133, 0xffff0000, v133
	v_lshlrev_b32_e32 v215, 16, v137
	v_and_b32_e32 v137, 0xffff0000, v137
	v_lshlrev_b32_e32 v224, 16, v134
	v_and_b32_e32 v134, 0xffff0000, v134
	v_lshlrev_b32_e32 v225, 16, v138
	v_and_b32_e32 v138, 0xffff0000, v138
	v_lshlrev_b32_e32 v234, 16, v135
	v_and_b32_e32 v135, 0xffff0000, v135
	v_lshlrev_b32_e32 v235, 16, v139
	v_and_b32_e32 v139, 0xffff0000, v139
	v_max_f32_e32 v168, 0xda24260, v168
	v_max_f32_e32 v132, 0xda24260, v132
	v_max_f32_e32 v214, 0xda24260, v214
	v_max_f32_e32 v133, 0xda24260, v133
	v_max_f32_e32 v224, 0xda24260, v224
	v_max_f32_e32 v134, 0xda24260, v134
	v_max_f32_e32 v234, 0xda24260, v234
	v_max_f32_e32 v135, 0xda24260, v135
	v_rcp_f32_e32 v168, v168
	v_rcp_f32_e32 v132, v132
	v_rcp_f32_e32 v214, v214
	v_rcp_f32_e32 v133, v133
	v_rcp_f32_e32 v224, v224
	v_rcp_f32_e32 v134, v134
	v_rcp_f32_e32 v234, v234
	v_rcp_f32_e32 v135, v135
	v_mul_f32_e32 v168, v168, v169
	v_mul_f32_e32 v132, v132, v136
	v_mul_f32_e32 v214, v214, v215
	v_mul_f32_e32 v133, v133, v137
	v_mul_f32_e32 v224, v224, v225
	v_mul_f32_e32 v134, v134, v138
	v_mul_f32_e32 v234, v234, v235
	v_mul_f32_e32 v135, v135, v139
	v_mul_f32_e32 v96, v96, v168
	v_mul_f32_e32 v97, v97, v132
	v_mul_f32_e32 v98, v98, v214
	v_mul_f32_e32 v99, v99, v133
	v_mul_f32_e32 v92, v92, v224
	v_mul_f32_e32 v93, v93, v134
	v_mul_f32_e32 v94, v94, v234
	v_mul_f32_e32 v95, v95, v135
	s_waitcnt vmcnt(12)
	v_lshlrev_b32_e32 v168, 16, v140
	v_and_b32_e32 v140, 0xffff0000, v140
	v_lshlrev_b32_e32 v169, 16, v144
	v_and_b32_e32 v144, 0xffff0000, v144
	v_lshlrev_b32_e32 v214, 16, v141
	v_and_b32_e32 v141, 0xffff0000, v141
	v_lshlrev_b32_e32 v215, 16, v145
	v_and_b32_e32 v145, 0xffff0000, v145
	v_lshlrev_b32_e32 v224, 16, v142
	v_and_b32_e32 v142, 0xffff0000, v142
	v_lshlrev_b32_e32 v225, 16, v146
	v_and_b32_e32 v146, 0xffff0000, v146
	v_lshlrev_b32_e32 v234, 16, v143
	v_and_b32_e32 v143, 0xffff0000, v143
	v_lshlrev_b32_e32 v235, 16, v147
	v_and_b32_e32 v147, 0xffff0000, v147
	v_max_f32_e32 v168, 0xda24260, v168
	v_max_f32_e32 v140, 0xda24260, v140
	v_max_f32_e32 v214, 0xda24260, v214
	v_max_f32_e32 v141, 0xda24260, v141
	v_max_f32_e32 v224, 0xda24260, v224
	v_max_f32_e32 v142, 0xda24260, v142
	v_max_f32_e32 v234, 0xda24260, v234
	v_max_f32_e32 v143, 0xda24260, v143
	v_rcp_f32_e32 v168, v168
	v_rcp_f32_e32 v140, v140
	v_rcp_f32_e32 v214, v214
	v_rcp_f32_e32 v141, v141
	v_rcp_f32_e32 v224, v224
	v_rcp_f32_e32 v142, v142
	v_rcp_f32_e32 v234, v234
	v_rcp_f32_e32 v143, v143
	v_mul_f32_e32 v168, v168, v169
	v_mul_f32_e32 v140, v140, v144
	v_mul_f32_e32 v214, v214, v215
	v_mul_f32_e32 v141, v141, v145
	v_mul_f32_e32 v224, v224, v225
	v_mul_f32_e32 v142, v142, v146
	v_mul_f32_e32 v234, v234, v235
	v_mul_f32_e32 v143, v143, v147
	v_mul_f32_e32 v88, v88, v168
	v_mul_f32_e32 v89, v89, v140
	v_mul_f32_e32 v90, v90, v214
	v_mul_f32_e32 v91, v91, v141
	v_mul_f32_e32 v84, v84, v224
	v_mul_f32_e32 v85, v85, v142
	v_mul_f32_e32 v86, v86, v234
	v_mul_f32_e32 v87, v87, v143
	s_waitcnt vmcnt(10)
	v_lshlrev_b32_e32 v168, 16, v148
	v_and_b32_e32 v148, 0xffff0000, v148
	v_lshlrev_b32_e32 v169, 16, v152
	v_and_b32_e32 v152, 0xffff0000, v152
	v_lshlrev_b32_e32 v214, 16, v149
	v_and_b32_e32 v149, 0xffff0000, v149
	v_lshlrev_b32_e32 v215, 16, v153
	v_and_b32_e32 v153, 0xffff0000, v153
	v_lshlrev_b32_e32 v224, 16, v150
	v_and_b32_e32 v150, 0xffff0000, v150
	v_lshlrev_b32_e32 v225, 16, v154
	v_and_b32_e32 v154, 0xffff0000, v154
	v_lshlrev_b32_e32 v234, 16, v151
	v_and_b32_e32 v151, 0xffff0000, v151
	v_lshlrev_b32_e32 v235, 16, v155
	v_and_b32_e32 v155, 0xffff0000, v155
	v_max_f32_e32 v168, 0xda24260, v168
	v_max_f32_e32 v148, 0xda24260, v148
	v_max_f32_e32 v214, 0xda24260, v214
	v_max_f32_e32 v149, 0xda24260, v149
	v_max_f32_e32 v224, 0xda24260, v224
	v_max_f32_e32 v150, 0xda24260, v150
	v_max_f32_e32 v234, 0xda24260, v234
	v_max_f32_e32 v151, 0xda24260, v151
	v_rcp_f32_e32 v168, v168
	v_rcp_f32_e32 v148, v148
	v_rcp_f32_e32 v214, v214
	v_rcp_f32_e32 v149, v149
	v_rcp_f32_e32 v224, v224
	v_rcp_f32_e32 v150, v150
	v_rcp_f32_e32 v234, v234
	v_rcp_f32_e32 v151, v151
	v_mul_f32_e32 v168, v168, v169
	v_mul_f32_e32 v148, v148, v152
	v_mul_f32_e32 v214, v214, v215
	v_mul_f32_e32 v149, v149, v153
	v_mul_f32_e32 v224, v224, v225
	v_mul_f32_e32 v150, v150, v154
	v_mul_f32_e32 v234, v234, v235
	v_mul_f32_e32 v151, v151, v155
	v_mul_f32_e32 v80, v80, v168
	v_mul_f32_e32 v81, v81, v148
	v_mul_f32_e32 v82, v82, v214
	v_mul_f32_e32 v83, v83, v149
	v_mul_f32_e32 v76, v76, v224
	v_mul_f32_e32 v77, v77, v150
	v_mul_f32_e32 v78, v78, v234
	v_mul_f32_e32 v79, v79, v151
	s_waitcnt vmcnt(8)
	v_lshlrev_b32_e32 v168, 16, v156
	v_and_b32_e32 v156, 0xffff0000, v156
	v_lshlrev_b32_e32 v169, 16, v160
	v_and_b32_e32 v160, 0xffff0000, v160
	v_lshlrev_b32_e32 v214, 16, v157
	v_and_b32_e32 v157, 0xffff0000, v157
	v_lshlrev_b32_e32 v215, 16, v161
	v_and_b32_e32 v161, 0xffff0000, v161
	v_lshlrev_b32_e32 v224, 16, v158
	v_and_b32_e32 v158, 0xffff0000, v158
	v_lshlrev_b32_e32 v225, 16, v162
	v_and_b32_e32 v162, 0xffff0000, v162
	v_lshlrev_b32_e32 v234, 16, v159
	v_and_b32_e32 v159, 0xffff0000, v159
	v_lshlrev_b32_e32 v235, 16, v163
	v_and_b32_e32 v163, 0xffff0000, v163
	v_max_f32_e32 v168, 0xda24260, v168
	v_max_f32_e32 v156, 0xda24260, v156
	v_max_f32_e32 v214, 0xda24260, v214
	v_max_f32_e32 v157, 0xda24260, v157
	v_max_f32_e32 v224, 0xda24260, v224
	v_max_f32_e32 v158, 0xda24260, v158
	v_max_f32_e32 v234, 0xda24260, v234
	v_max_f32_e32 v159, 0xda24260, v159
	v_rcp_f32_e32 v168, v168
	v_rcp_f32_e32 v156, v156
	v_rcp_f32_e32 v214, v214
	v_rcp_f32_e32 v157, v157
	v_rcp_f32_e32 v224, v224
	v_rcp_f32_e32 v158, v158
	v_rcp_f32_e32 v234, v234
	v_rcp_f32_e32 v159, v159
	v_mul_f32_e32 v168, v168, v169
	v_mul_f32_e32 v156, v156, v160
	v_mul_f32_e32 v214, v214, v215
	v_mul_f32_e32 v157, v157, v161
	v_mul_f32_e32 v224, v224, v225
	v_mul_f32_e32 v158, v158, v162
	v_mul_f32_e32 v234, v234, v235
	v_mul_f32_e32 v159, v159, v163
	v_mul_f32_e32 v72, v72, v168
	v_mul_f32_e32 v73, v73, v156
	v_mul_f32_e32 v74, v74, v214
	v_mul_f32_e32 v75, v75, v157
	v_mul_f32_e32 v68, v68, v224
	v_mul_f32_e32 v69, v69, v158
	v_mul_f32_e32 v70, v70, v234
	v_mul_f32_e32 v71, v71, v159
	s_waitcnt vmcnt(6)
	v_lshlrev_b32_e32 v168, 16, v180
	v_and_b32_e32 v180, 0xffff0000, v180
	v_lshlrev_b32_e32 v169, 16, v184
	v_and_b32_e32 v184, 0xffff0000, v184
	v_lshlrev_b32_e32 v214, 16, v181
	v_and_b32_e32 v181, 0xffff0000, v181
	v_lshlrev_b32_e32 v215, 16, v185
	v_and_b32_e32 v185, 0xffff0000, v185
	v_lshlrev_b32_e32 v224, 16, v182
	v_and_b32_e32 v182, 0xffff0000, v182
	v_lshlrev_b32_e32 v225, 16, v186
	v_and_b32_e32 v186, 0xffff0000, v186
	v_lshlrev_b32_e32 v234, 16, v183
	v_and_b32_e32 v183, 0xffff0000, v183
	v_lshlrev_b32_e32 v235, 16, v187
	v_and_b32_e32 v187, 0xffff0000, v187
	v_max_f32_e32 v168, 0xda24260, v168
	v_max_f32_e32 v180, 0xda24260, v180
	v_max_f32_e32 v214, 0xda24260, v214
	v_max_f32_e32 v181, 0xda24260, v181
	v_max_f32_e32 v224, 0xda24260, v224
	v_max_f32_e32 v182, 0xda24260, v182
	v_max_f32_e32 v234, 0xda24260, v234
	v_max_f32_e32 v183, 0xda24260, v183
	v_rcp_f32_e32 v168, v168
	v_rcp_f32_e32 v180, v180
	v_rcp_f32_e32 v214, v214
	v_rcp_f32_e32 v181, v181
	v_rcp_f32_e32 v224, v224
	v_rcp_f32_e32 v182, v182
	v_rcp_f32_e32 v234, v234
	v_rcp_f32_e32 v183, v183
	v_mul_f32_e32 v168, v168, v169
	v_mul_f32_e32 v180, v180, v184
	v_mul_f32_e32 v214, v214, v215
	v_mul_f32_e32 v181, v181, v185
	v_mul_f32_e32 v224, v224, v225
	v_mul_f32_e32 v182, v182, v186
	v_mul_f32_e32 v234, v234, v235
	v_mul_f32_e32 v183, v183, v187
	v_mul_f32_e32 v32, v32, v168
	v_mul_f32_e32 v33, v33, v180
	v_mul_f32_e32 v34, v34, v214
	v_mul_f32_e32 v35, v35, v181
	v_mul_f32_e32 v28, v28, v224
	v_mul_f32_e32 v29, v29, v182
	v_mul_f32_e32 v30, v30, v234
	v_mul_f32_e32 v31, v31, v183
	s_waitcnt vmcnt(4)
	v_lshlrev_b32_e32 v168, 16, v188
	v_and_b32_e32 v188, 0xffff0000, v188
	v_lshlrev_b32_e32 v169, 16, v192
	v_and_b32_e32 v192, 0xffff0000, v192
	v_lshlrev_b32_e32 v214, 16, v189
	v_and_b32_e32 v189, 0xffff0000, v189
	v_lshlrev_b32_e32 v215, 16, v193
	v_and_b32_e32 v193, 0xffff0000, v193
	v_lshlrev_b32_e32 v224, 16, v190
	v_and_b32_e32 v190, 0xffff0000, v190
	v_lshlrev_b32_e32 v225, 16, v194
	v_and_b32_e32 v194, 0xffff0000, v194
	v_lshlrev_b32_e32 v234, 16, v191
	v_and_b32_e32 v191, 0xffff0000, v191
	v_lshlrev_b32_e32 v235, 16, v195
	v_and_b32_e32 v195, 0xffff0000, v195
	v_max_f32_e32 v168, 0xda24260, v168
	v_max_f32_e32 v188, 0xda24260, v188
	v_max_f32_e32 v214, 0xda24260, v214
	v_max_f32_e32 v189, 0xda24260, v189
	v_max_f32_e32 v224, 0xda24260, v224
	v_max_f32_e32 v190, 0xda24260, v190
	v_max_f32_e32 v234, 0xda24260, v234
	v_max_f32_e32 v191, 0xda24260, v191
	v_rcp_f32_e32 v168, v168
	v_rcp_f32_e32 v188, v188
	v_rcp_f32_e32 v214, v214
	v_rcp_f32_e32 v189, v189
	v_rcp_f32_e32 v224, v224
	v_rcp_f32_e32 v190, v190
	v_rcp_f32_e32 v234, v234
	v_rcp_f32_e32 v191, v191
	v_mul_f32_e32 v168, v168, v169
	v_mul_f32_e32 v188, v188, v192
	v_mul_f32_e32 v214, v214, v215
	v_mul_f32_e32 v189, v189, v193
	v_mul_f32_e32 v224, v224, v225
	v_mul_f32_e32 v190, v190, v194
	v_mul_f32_e32 v234, v234, v235
	v_mul_f32_e32 v191, v191, v195
	v_mul_f32_e32 v24, v24, v168
	v_mul_f32_e32 v25, v25, v188
	v_mul_f32_e32 v26, v26, v214
	v_mul_f32_e32 v27, v27, v189
	v_mul_f32_e32 v20, v20, v224
	v_mul_f32_e32 v21, v21, v190
	v_mul_f32_e32 v22, v22, v234
	v_mul_f32_e32 v23, v23, v191
	s_waitcnt vmcnt(2)
	v_lshlrev_b32_e32 v168, 16, v200
	v_and_b32_e32 v200, 0xffff0000, v200
	v_lshlrev_b32_e32 v169, 16, v204
	v_and_b32_e32 v204, 0xffff0000, v204
	v_lshlrev_b32_e32 v214, 16, v201
	v_and_b32_e32 v201, 0xffff0000, v201
	v_lshlrev_b32_e32 v215, 16, v205
	v_and_b32_e32 v205, 0xffff0000, v205
	v_lshlrev_b32_e32 v224, 16, v202
	v_and_b32_e32 v202, 0xffff0000, v202
	v_lshlrev_b32_e32 v225, 16, v206
	v_and_b32_e32 v206, 0xffff0000, v206
	v_lshlrev_b32_e32 v234, 16, v203
	v_and_b32_e32 v203, 0xffff0000, v203
	v_lshlrev_b32_e32 v235, 16, v207
	v_and_b32_e32 v207, 0xffff0000, v207
	v_max_f32_e32 v168, 0xda24260, v168
	v_max_f32_e32 v200, 0xda24260, v200
	v_max_f32_e32 v214, 0xda24260, v214
	v_max_f32_e32 v201, 0xda24260, v201
	v_max_f32_e32 v224, 0xda24260, v224
	v_max_f32_e32 v202, 0xda24260, v202
	v_max_f32_e32 v234, 0xda24260, v234
	v_max_f32_e32 v203, 0xda24260, v203
	v_rcp_f32_e32 v168, v168
	v_rcp_f32_e32 v200, v200
	v_rcp_f32_e32 v214, v214
	v_rcp_f32_e32 v201, v201
	v_rcp_f32_e32 v224, v224
	v_rcp_f32_e32 v202, v202
	v_rcp_f32_e32 v234, v234
	v_rcp_f32_e32 v203, v203
	v_mul_f32_e32 v168, v168, v169
	v_mul_f32_e32 v200, v200, v204
	v_mul_f32_e32 v214, v214, v215
	v_mul_f32_e32 v201, v201, v205
	v_mul_f32_e32 v224, v224, v225
	v_mul_f32_e32 v202, v202, v206
	v_mul_f32_e32 v234, v234, v235
	v_mul_f32_e32 v203, v203, v207
	v_mul_f32_e32 v16, v16, v168
	v_mul_f32_e32 v17, v17, v200
	v_mul_f32_e32 v18, v18, v214
	v_mul_f32_e32 v19, v19, v201
	v_mul_f32_e32 v12, v12, v224
	v_mul_f32_e32 v13, v13, v202
	v_mul_f32_e32 v14, v14, v234
	v_mul_f32_e32 v15, v15, v203
	s_waitcnt vmcnt(0)
	v_lshlrev_b32_e32 v168, 16, v208
	v_and_b32_e32 v208, 0xffff0000, v208
	v_lshlrev_b32_e32 v169, 16, v220
	v_and_b32_e32 v220, 0xffff0000, v220
	v_lshlrev_b32_e32 v214, 16, v209
	v_and_b32_e32 v209, 0xffff0000, v209
	v_lshlrev_b32_e32 v215, 16, v221
	v_and_b32_e32 v221, 0xffff0000, v221
	v_lshlrev_b32_e32 v224, 16, v210
	v_and_b32_e32 v210, 0xffff0000, v210
	v_lshlrev_b32_e32 v225, 16, v222
	v_and_b32_e32 v222, 0xffff0000, v222
	v_lshlrev_b32_e32 v234, 16, v211
	v_and_b32_e32 v211, 0xffff0000, v211
	v_lshlrev_b32_e32 v235, 16, v223
	v_and_b32_e32 v223, 0xffff0000, v223
	v_max_f32_e32 v168, 0xda24260, v168
	v_max_f32_e32 v208, 0xda24260, v208
	v_max_f32_e32 v214, 0xda24260, v214
	v_max_f32_e32 v209, 0xda24260, v209
	v_max_f32_e32 v224, 0xda24260, v224
	v_max_f32_e32 v210, 0xda24260, v210
	v_max_f32_e32 v234, 0xda24260, v234
	v_max_f32_e32 v211, 0xda24260, v211
	v_rcp_f32_e32 v168, v168
	v_rcp_f32_e32 v208, v208
	v_rcp_f32_e32 v214, v214
	v_rcp_f32_e32 v209, v209
	v_rcp_f32_e32 v224, v224
	v_rcp_f32_e32 v210, v210
	v_rcp_f32_e32 v234, v234
	v_rcp_f32_e32 v211, v211
	v_mul_f32_e32 v168, v168, v169
	v_mul_f32_e32 v208, v208, v220
	v_mul_f32_e32 v214, v214, v215
	v_mul_f32_e32 v209, v209, v221
	v_mul_f32_e32 v224, v224, v225
	v_mul_f32_e32 v210, v210, v222
	v_mul_f32_e32 v234, v234, v235
	v_mul_f32_e32 v211, v211, v223
	v_mul_f32_e32 v8, v8, v168
	v_mul_f32_e32 v9, v9, v208
	v_mul_f32_e32 v10, v10, v214
	v_mul_f32_e32 v11, v11, v209
	v_mul_f32_e32 v4, v4, v224
	v_mul_f32_e32 v5, v5, v210
	v_mul_f32_e32 v6, v6, v234
	v_mul_f32_e32 v7, v7, v211
	s_mov_b64 s[40:41], -1
	s_branch .Lg2e_done
.Lg2e_k1:
	s_add_u32 s4, s2, 0x0
	s_addc_u32 s5, s3, 0
	global_load_dwordx4 v[132:135], v199, s[4:5]
	s_add_u32 s4, s2, 0x8000
	s_addc_u32 s5, s3, 0
	global_load_dwordx4 v[136:139], v199, s[4:5]
	s_add_u32 s4, s2, 0x10000
	s_addc_u32 s5, s3, 0
	global_load_dwordx4 v[140:143], v199, s[4:5]
	s_add_u32 s4, s2, 0x18000
	s_addc_u32 s5, s3, 0
	global_load_dwordx4 v[144:147], v199, s[4:5]
	s_add_u32 s4, s2, 0x40000
	s_addc_u32 s5, s3, 0
	global_load_dwordx4 v[148:151], v199, s[4:5]
	s_add_u32 s4, s2, 0x48000
	s_addc_u32 s5, s3, 0
	global_load_dwordx4 v[152:155], v199, s[4:5]
	s_add_u32 s4, s2, 0x50000
	s_addc_u32 s5, s3, 0
	global_load_dwordx4 v[156:159], v199, s[4:5]
	s_add_u32 s4, s2, 0x58000
	s_addc_u32 s5, s3, 0
	global_load_dwordx4 v[160:163], v199, s[4:5]
	s_add_u32 s4, s2, 0x0
	s_addc_u32 s5, s3, 0
	global_load_dwordx4 v[180:183], v199, s[4:5] offset:256
	s_add_u32 s4, s2, 0x8000
	s_addc_u32 s5, s3, 0
	global_load_dwordx4 v[184:187], v199, s[4:5] offset:256
	s_add_u32 s4, s2, 0x10000
	s_addc_u32 s5, s3, 0
	global_load_dwordx4 v[188:191], v199, s[4:5] offset:256
	s_add_u32 s4, s2, 0x18000
	s_addc_u32 s5, s3, 0
	global_load_dwordx4 v[192:195], v199, s[4:5] offset:256
	s_add_u32 s4, s2, 0x40000
	s_addc_u32 s5, s3, 0
	global_load_dwordx4 v[200:203], v199, s[4:5] offset:256
	s_add_u32 s4, s2, 0x48000
	s_addc_u32 s5, s3, 0
	global_load_dwordx4 v[204:207], v199, s[4:5] offset:256
	s_add_u32 s4, s2, 0x50000
	s_addc_u32 s5, s3, 0
	global_load_dwordx4 v[208:211], v199, s[4:5] offset:256
	s_add_u32 s4, s2, 0x58000
	s_addc_u32 s5, s3, 0
	global_load_dwordx4 v[220:223], v199, s[4:5] offset:256
	s_waitcnt vmcnt(15)
	v_lshlrev_b32_e32 v168, 16, v132
	v_and_b32_e32 v132, 0xffff0000, v132
	v_lshlrev_b32_e32 v169, 16, v133
	v_and_b32_e32 v133, 0xffff0000, v133
	v_lshlrev_b32_e32 v214, 16, v134
	v_and_b32_e32 v134, 0xffff0000, v134
	v_lshlrev_b32_e32 v215, 16, v135
	v_and_b32_e32 v135, 0xffff0000, v135
	v_mul_f32_e32 v168, v128, v168
	v_mul_f32_e32 v132, v129, v132
	v_mul_f32_e32 v169, v130, v169
	v_mul_f32_e32 v133, v131, v133
	v_mul_f32_e32 v214, v124, v214
	v_mul_f32_e32 v134, v125, v134
	v_mul_f32_e32 v215, v126, v215
	v_mul_f32_e32 v135, v127, v135
	v_cvt_pk_bf16_f32 v132, v168, v132
	v_cvt_pk_bf16_f32 v133, v169, v133
	v_cvt_pk_bf16_f32 v134, v214, v134
	v_cvt_pk_bf16_f32 v135, v215, v135
	s_add_u32 s40, s68, 0x0
	s_addc_u32 s41, s69, 0
	global_store_dwordx4 v199, v[132:135], s[40:41]
	s_waitcnt vmcnt(15)
	v_lshlrev_b32_e32 v168, 16, v136
	v_and_b32_e32 v136, 0xffff0000, v136
	v_lshlrev_b32_e32 v169, 16, v137
	v_and_b32_e32 v137, 0xffff0000, v137
	v_lshlrev_b32_e32 v214, 16, v138
	v_and_b32_e32 v138, 0xffff0000, v138
	v_lshlrev_b32_e32 v215, 16, v139
	v_and_b32_e32 v139, 0xffff0000, v139
	v_mul_f32_e32 v168, v120, v168
	v_mul_f32_e32 v136, v121, v136
	v_mul_f32_e32 v169, v122, v169
	v_mul_f32_e32 v137, v123, v137
	v_mul_f32_e32 v214, v116, v214
	v_mul_f32_e32 v138, v117, v138
	v_mul_f32_e32 v215, v118, v215
	v_mul_f32_e32 v139, v119, v139
	v_cvt_pk_bf16_f32 v136, v168, v136
	v_cvt_pk_bf16_f32 v137, v169, v137
	v_cvt_pk_bf16_f32 v138, v214, v138
	v_cvt_pk_bf16_f32 v139, v215, v139
	s_add_u32 s40, s68, 0x8000
	s_addc_u32 s41, s69, 0
	global_store_dwordx4 v199, v[136:139], s[40:41]
	s_waitcnt vmcnt(15)
	v_lshlrev_b32_e32 v168, 16, v140
	v_and_b32_e32 v140, 0xffff0000, v140
	v_lshlrev_b32_e32 v169, 16, v141
	v_and_b32_e32 v141, 0xffff0000, v141
	v_lshlrev_b32_e32 v214, 16, v142
	v_and_b32_e32 v142, 0xffff0000, v142
	v_lshlrev_b32_e32 v215, 16, v143
	v_and_b32_e32 v143, 0xffff0000, v143
	v_mul_f32_e32 v168, v112, v168
	v_mul_f32_e32 v140, v113, v140
	v_mul_f32_e32 v169, v114, v169
	v_mul_f32_e32 v141, v115, v141
	v_mul_f32_e32 v214, v108, v214
	v_mul_f32_e32 v142, v109, v142
	v_mul_f32_e32 v215, v110, v215
	v_mul_f32_e32 v143, v111, v143
	v_cvt_pk_bf16_f32 v140, v168, v140
	v_cvt_pk_bf16_f32 v141, v169, v141
	v_cvt_pk_bf16_f32 v142, v214, v142
	v_cvt_pk_bf16_f32 v143, v215, v143
	s_add_u32 s40, s68, 0x10000
	s_addc_u32 s41, s69, 0
	global_store_dwordx4 v199, v[140:143], s[40:41]
	s_waitcnt vmcnt(15)
	v_lshlrev_b32_e32 v168, 16, v144
	v_and_b32_e32 v144, 0xffff0000, v144
	v_lshlrev_b32_e32 v169, 16, v145
	v_and_b32_e32 v145, 0xffff0000, v145
	v_lshlrev_b32_e32 v214, 16, v146
	v_and_b32_e32 v146, 0xffff0000, v146
	v_lshlrev_b32_e32 v215, 16, v147
	v_and_b32_e32 v147, 0xffff0000, v147
	v_mul_f32_e32 v168, v104, v168
	v_mul_f32_e32 v144, v105, v144
	v_mul_f32_e32 v169, v106, v169
	v_mul_f32_e32 v145, v107, v145
	v_mul_f32_e32 v214, v100, v214
	v_mul_f32_e32 v146, v101, v146
	v_mul_f32_e32 v215, v102, v215
	v_mul_f32_e32 v147, v103, v147
	v_cvt_pk_bf16_f32 v144, v168, v144
	v_cvt_pk_bf16_f32 v145, v169, v145
	v_cvt_pk_bf16_f32 v146, v214, v146
	v_cvt_pk_bf16_f32 v147, v215, v147
	s_add_u32 s40, s68, 0x18000
	s_addc_u32 s41, s69, 0
	global_store_dwordx4 v199, v[144:147], s[40:41]
	s_waitcnt vmcnt(15)
	v_lshlrev_b32_e32 v168, 16, v148
	v_and_b32_e32 v148, 0xffff0000, v148
	v_lshlrev_b32_e32 v169, 16, v149
	v_and_b32_e32 v149, 0xffff0000, v149
	v_lshlrev_b32_e32 v214, 16, v150
	v_and_b32_e32 v150, 0xffff0000, v150
	v_lshlrev_b32_e32 v215, 16, v151
	v_and_b32_e32 v151, 0xffff0000, v151
	v_mul_f32_e32 v168, v64, v168
	v_mul_f32_e32 v148, v65, v148
	v_mul_f32_e32 v169, v66, v169
	v_mul_f32_e32 v149, v67, v149
	v_mul_f32_e32 v214, v60, v214
	v_mul_f32_e32 v150, v61, v150
	v_mul_f32_e32 v215, v62, v215
	v_mul_f32_e32 v151, v63, v151
	v_cvt_pk_bf16_f32 v148, v168, v148
	v_cvt_pk_bf16_f32 v149, v169, v149
	v_cvt_pk_bf16_f32 v150, v214, v150
	v_cvt_pk_bf16_f32 v151, v215, v151
	s_add_u32 s40, s68, 0x40000
	s_addc_u32 s41, s69, 0
	global_store_dwordx4 v199, v[148:151], s[40:41]
	s_waitcnt vmcnt(15)
	v_lshlrev_b32_e32 v168, 16, v152
	v_and_b32_e32 v152, 0xffff0000, v152
	v_lshlrev_b32_e32 v169, 16, v153
	v_and_b32_e32 v153, 0xffff0000, v153
	v_lshlrev_b32_e32 v214, 16, v154
	v_and_b32_e32 v154, 0xffff0000, v154
	v_lshlrev_b32_e32 v215, 16, v155
	v_and_b32_e32 v155, 0xffff0000, v155
	v_mul_f32_e32 v168, v56, v168
	v_mul_f32_e32 v152, v57, v152
	v_mul_f32_e32 v169, v58, v169
	v_mul_f32_e32 v153, v59, v153
	v_mul_f32_e32 v214, v52, v214
	v_mul_f32_e32 v154, v53, v154
	v_mul_f32_e32 v215, v54, v215
	v_mul_f32_e32 v155, v55, v155
	v_cvt_pk_bf16_f32 v152, v168, v152
	v_cvt_pk_bf16_f32 v153, v169, v153
	v_cvt_pk_bf16_f32 v154, v214, v154
	v_cvt_pk_bf16_f32 v155, v215, v155
	s_add_u32 s40, s68, 0x48000
	s_addc_u32 s41, s69, 0
	global_store_dwordx4 v199, v[152:155], s[40:41]
	s_waitcnt vmcnt(15)
	v_lshlrev_b32_e32 v168, 16, v156
	v_and_b32_e32 v156, 0xffff0000, v156
	v_lshlrev_b32_e32 v169, 16, v157
	v_and_b32_e32 v157, 0xffff0000, v157
	v_lshlrev_b32_e32 v214, 16, v158
	v_and_b32_e32 v158, 0xffff0000, v158
	v_lshlrev_b32_e32 v215, 16, v159
	v_and_b32_e32 v159, 0xffff0000, v159
	v_mul_f32_e32 v168, v48, v168
	v_mul_f32_e32 v156, v49, v156
	v_mul_f32_e32 v169, v50, v169
	v_mul_f32_e32 v157, v51, v157
	v_mul_f32_e32 v214, v44, v214
	v_mul_f32_e32 v158, v45, v158
	v_mul_f32_e32 v215, v46, v215
	v_mul_f32_e32 v159, v47, v159
	v_cvt_pk_bf16_f32 v156, v168, v156
	v_cvt_pk_bf16_f32 v157, v169, v157
	v_cvt_pk_bf16_f32 v158, v214, v158
	v_cvt_pk_bf16_f32 v159, v215, v159
	s_add_u32 s40, s68, 0x50000
	s_addc_u32 s41, s69, 0
	global_store_dwordx4 v199, v[156:159], s[40:41]
	s_waitcnt vmcnt(15)
	v_lshlrev_b32_e32 v168, 16, v160
	v_and_b32_e32 v160, 0xffff0000, v160
	v_lshlrev_b32_e32 v169, 16, v161
	v_and_b32_e32 v161, 0xffff0000, v161
	v_lshlrev_b32_e32 v214, 16, v162
	v_and_b32_e32 v162, 0xffff0000, v162
	v_lshlrev_b32_e32 v215, 16, v163
	v_and_b32_e32 v163, 0xffff0000, v163
	v_mul_f32_e32 v168, v40, v168
	v_mul_f32_e32 v160, v41, v160
	v_mul_f32_e32 v169, v42, v169
	v_mul_f32_e32 v161, v43, v161
	v_mul_f32_e32 v214, v36, v214
	v_mul_f32_e32 v162, v37, v162
	v_mul_f32_e32 v215, v38, v215
	v_mul_f32_e32 v163, v39, v163
	v_cvt_pk_bf16_f32 v160, v168, v160
	v_cvt_pk_bf16_f32 v161, v169, v161
	v_cvt_pk_bf16_f32 v162, v214, v162
	v_cvt_pk_bf16_f32 v163, v215, v163
	s_add_u32 s40, s68, 0x58000
	s_addc_u32 s41, s69, 0
	global_store_dwordx4 v199, v[160:163], s[40:41]
	s_waitcnt vmcnt(15)
	v_lshlrev_b32_e32 v168, 16, v180
	v_and_b32_e32 v180, 0xffff0000, v180
	v_lshlrev_b32_e32 v169, 16, v181
	v_and_b32_e32 v181, 0xffff0000, v181
	v_lshlrev_b32_e32 v214, 16, v182
	v_and_b32_e32 v182, 0xffff0000, v182
	v_lshlrev_b32_e32 v215, 16, v183
	v_and_b32_e32 v183, 0xffff0000, v183
	v_mul_f32_e32 v168, v96, v168
	v_mul_f32_e32 v180, v97, v180
	v_mul_f32_e32 v169, v98, v169
	v_mul_f32_e32 v181, v99, v181
	v_mul_f32_e32 v214, v92, v214
	v_mul_f32_e32 v182, v93, v182
	v_mul_f32_e32 v215, v94, v215
	v_mul_f32_e32 v183, v95, v183
	v_cvt_pk_bf16_f32 v180, v168, v180
	v_cvt_pk_bf16_f32 v181, v169, v181
	v_cvt_pk_bf16_f32 v182, v214, v182
	v_cvt_pk_bf16_f32 v183, v215, v183
	s_add_u32 s40, s68, 0x0
	s_addc_u32 s41, s69, 0
	global_store_dwordx4 v199, v[180:183], s[40:41] offset:256
	s_waitcnt vmcnt(15)
	v_lshlrev_b32_e32 v168, 16, v184
	v_and_b32_e32 v184, 0xffff0000, v184
	v_lshlrev_b32_e32 v169, 16, v185
	v_and_b32_e32 v185, 0xffff0000, v185
	v_lshlrev_b32_e32 v214, 16, v186
	v_and_b32_e32 v186, 0xffff0000, v186
	v_lshlrev_b32_e32 v215, 16, v187
	v_and_b32_e32 v187, 0xffff0000, v187
	v_mul_f32_e32 v168, v88, v168
	v_mul_f32_e32 v184, v89, v184
	v_mul_f32_e32 v169, v90, v169
	v_mul_f32_e32 v185, v91, v185
	v_mul_f32_e32 v214, v84, v214
	v_mul_f32_e32 v186, v85, v186
	v_mul_f32_e32 v215, v86, v215
	v_mul_f32_e32 v187, v87, v187
	v_cvt_pk_bf16_f32 v184, v168, v184
	v_cvt_pk_bf16_f32 v185, v169, v185
	v_cvt_pk_bf16_f32 v186, v214, v186
	v_cvt_pk_bf16_f32 v187, v215, v187
	s_add_u32 s40, s68, 0x8000
	s_addc_u32 s41, s69, 0
	global_store_dwordx4 v199, v[184:187], s[40:41] offset:256
	s_waitcnt vmcnt(15)
	v_lshlrev_b32_e32 v168, 16, v188
	v_and_b32_e32 v188, 0xffff0000, v188
	v_lshlrev_b32_e32 v169, 16, v189
	v_and_b32_e32 v189, 0xffff0000, v189
	v_lshlrev_b32_e32 v214, 16, v190
	v_and_b32_e32 v190, 0xffff0000, v190
	v_lshlrev_b32_e32 v215, 16, v191
	v_and_b32_e32 v191, 0xffff0000, v191
	v_mul_f32_e32 v168, v80, v168
	v_mul_f32_e32 v188, v81, v188
	v_mul_f32_e32 v169, v82, v169
	v_mul_f32_e32 v189, v83, v189
	v_mul_f32_e32 v214, v76, v214
	v_mul_f32_e32 v190, v77, v190
	v_mul_f32_e32 v215, v78, v215
	v_mul_f32_e32 v191, v79, v191
	v_cvt_pk_bf16_f32 v188, v168, v188
	v_cvt_pk_bf16_f32 v189, v169, v189
	v_cvt_pk_bf16_f32 v190, v214, v190
	v_cvt_pk_bf16_f32 v191, v215, v191
	s_add_u32 s40, s68, 0x10000
	s_addc_u32 s41, s69, 0
	global_store_dwordx4 v199, v[188:191], s[40:41] offset:256
	s_waitcnt vmcnt(15)
	v_lshlrev_b32_e32 v168, 16, v192
	v_and_b32_e32 v192, 0xffff0000, v192
	v_lshlrev_b32_e32 v169, 16, v193
	v_and_b32_e32 v193, 0xffff0000, v193
	v_lshlrev_b32_e32 v214, 16, v194
	v_and_b32_e32 v194, 0xffff0000, v194
	v_lshlrev_b32_e32 v215, 16, v195
	v_and_b32_e32 v195, 0xffff0000, v195
	v_mul_f32_e32 v168, v72, v168
	v_mul_f32_e32 v192, v73, v192
	v_mul_f32_e32 v169, v74, v169
	v_mul_f32_e32 v193, v75, v193
	v_mul_f32_e32 v214, v68, v214
	v_mul_f32_e32 v194, v69, v194
	v_mul_f32_e32 v215, v70, v215
	v_mul_f32_e32 v195, v71, v195
	v_cvt_pk_bf16_f32 v192, v168, v192
	v_cvt_pk_bf16_f32 v193, v169, v193
	v_cvt_pk_bf16_f32 v194, v214, v194
	v_cvt_pk_bf16_f32 v195, v215, v195
	s_add_u32 s40, s68, 0x18000
	s_addc_u32 s41, s69, 0
	global_store_dwordx4 v199, v[192:195], s[40:41] offset:256
	s_waitcnt vmcnt(15)
	v_lshlrev_b32_e32 v168, 16, v200
	v_and_b32_e32 v200, 0xffff0000, v200
	v_lshlrev_b32_e32 v169, 16, v201
	v_and_b32_e32 v201, 0xffff0000, v201
	v_lshlrev_b32_e32 v214, 16, v202
	v_and_b32_e32 v202, 0xffff0000, v202
	v_lshlrev_b32_e32 v215, 16, v203
	v_and_b32_e32 v203, 0xffff0000, v203
	v_mul_f32_e32 v168, v32, v168
	v_mul_f32_e32 v200, v33, v200
	v_mul_f32_e32 v169, v34, v169
	v_mul_f32_e32 v201, v35, v201
	v_mul_f32_e32 v214, v28, v214
	v_mul_f32_e32 v202, v29, v202
	v_mul_f32_e32 v215, v30, v215
	v_mul_f32_e32 v203, v31, v203
	v_cvt_pk_bf16_f32 v200, v168, v200
	v_cvt_pk_bf16_f32 v201, v169, v201
	v_cvt_pk_bf16_f32 v202, v214, v202
	v_cvt_pk_bf16_f32 v203, v215, v203
	s_add_u32 s40, s68, 0x40000
	s_addc_u32 s41, s69, 0
	global_store_dwordx4 v199, v[200:203], s[40:41] offset:256
	s_waitcnt vmcnt(15)
	v_lshlrev_b32_e32 v168, 16, v204
	v_and_b32_e32 v204, 0xffff0000, v204
	v_lshlrev_b32_e32 v169, 16, v205
	v_and_b32_e32 v205, 0xffff0000, v205
	v_lshlrev_b32_e32 v214, 16, v206
	v_and_b32_e32 v206, 0xffff0000, v206
	v_lshlrev_b32_e32 v215, 16, v207
	v_and_b32_e32 v207, 0xffff0000, v207
	v_mul_f32_e32 v168, v24, v168
	v_mul_f32_e32 v204, v25, v204
	v_mul_f32_e32 v169, v26, v169
	v_mul_f32_e32 v205, v27, v205
	v_mul_f32_e32 v214, v20, v214
	v_mul_f32_e32 v206, v21, v206
	v_mul_f32_e32 v215, v22, v215
	v_mul_f32_e32 v207, v23, v207
	v_cvt_pk_bf16_f32 v204, v168, v204
	v_cvt_pk_bf16_f32 v205, v169, v205
	v_cvt_pk_bf16_f32 v206, v214, v206
	v_cvt_pk_bf16_f32 v207, v215, v207
	s_add_u32 s40, s68, 0x48000
	s_addc_u32 s41, s69, 0
	global_store_dwordx4 v199, v[204:207], s[40:41] offset:256
	s_waitcnt vmcnt(15)
	v_lshlrev_b32_e32 v168, 16, v208
	v_and_b32_e32 v208, 0xffff0000, v208
	v_lshlrev_b32_e32 v169, 16, v209
	v_and_b32_e32 v209, 0xffff0000, v209
	v_lshlrev_b32_e32 v214, 16, v210
	v_and_b32_e32 v210, 0xffff0000, v210
	v_lshlrev_b32_e32 v215, 16, v211
	v_and_b32_e32 v211, 0xffff0000, v211
	v_mul_f32_e32 v168, v16, v168
	v_mul_f32_e32 v208, v17, v208
	v_mul_f32_e32 v169, v18, v169
	v_mul_f32_e32 v209, v19, v209
	v_mul_f32_e32 v214, v12, v214
	v_mul_f32_e32 v210, v13, v210
	v_mul_f32_e32 v215, v14, v215
	v_mul_f32_e32 v211, v15, v211
	v_cvt_pk_bf16_f32 v208, v168, v208
	v_cvt_pk_bf16_f32 v209, v169, v209
	v_cvt_pk_bf16_f32 v210, v214, v210
	v_cvt_pk_bf16_f32 v211, v215, v211
	s_add_u32 s40, s68, 0x50000
	s_addc_u32 s41, s69, 0
	global_store_dwordx4 v199, v[208:211], s[40:41] offset:256
	s_waitcnt vmcnt(15)
	v_lshlrev_b32_e32 v168, 16, v220
	v_and_b32_e32 v220, 0xffff0000, v220
	v_lshlrev_b32_e32 v169, 16, v221
	v_and_b32_e32 v221, 0xffff0000, v221
	v_lshlrev_b32_e32 v214, 16, v222
	v_and_b32_e32 v222, 0xffff0000, v222
	v_lshlrev_b32_e32 v215, 16, v223
	v_and_b32_e32 v223, 0xffff0000, v223
	v_mul_f32_e32 v168, v8, v168
	v_mul_f32_e32 v220, v9, v220
	v_mul_f32_e32 v169, v10, v169
	v_mul_f32_e32 v221, v11, v221
	v_mul_f32_e32 v214, v4, v214
	v_mul_f32_e32 v222, v5, v222
	v_mul_f32_e32 v215, v6, v215
	v_mul_f32_e32 v223, v7, v223
	v_cvt_pk_bf16_f32 v220, v168, v220
	v_cvt_pk_bf16_f32 v221, v169, v221
	v_cvt_pk_bf16_f32 v222, v214, v222
	v_cvt_pk_bf16_f32 v223, v215, v223
	s_add_u32 s40, s68, 0x58000
	s_addc_u32 s41, s69, 0
	global_store_dwordx4 v199, v[220:223], s[40:41] offset:256
	s_mov_b64 s[40:41], 0
.Lg2e_done:
.LBB0_731:
	s_mov_b64 s[2:3], -1
	s_and_b64 vcc, exec, s[38:39]
	s_cbranch_vccz .LBB0_622
	s_and_b64 vcc, exec, s[40:41]
	s_cbranch_vccnz .LBB0_621
	v_mov_b32_e32 v4, 0
	v_mov_b32_e32 v5, v4
	v_mov_b32_e32 v6, v4
	v_mov_b32_e32 v7, v4
	v_mov_b32_e32 v8, v4
	v_mov_b32_e32 v9, v4
	v_mov_b32_e32 v10, v4
	v_mov_b32_e32 v11, v4
	v_mov_b32_e32 v12, v4
	v_mov_b32_e32 v13, v4
	v_mov_b32_e32 v14, v4
	v_mov_b32_e32 v15, v4
	v_mov_b32_e32 v16, v4
	v_mov_b32_e32 v17, v4
	v_mov_b32_e32 v18, v4
	v_mov_b32_e32 v19, v4
	v_mov_b32_e32 v20, v4
	v_mov_b32_e32 v21, v4
	v_mov_b32_e32 v22, v4
	v_mov_b32_e32 v23, v4
	v_mov_b32_e32 v24, v4
	v_mov_b32_e32 v25, v4
	v_mov_b32_e32 v26, v4
	v_mov_b32_e32 v27, v4
	v_mov_b32_e32 v28, v4
	v_mov_b32_e32 v29, v4
	v_mov_b32_e32 v30, v4
	v_mov_b32_e32 v31, v4
	v_mov_b32_e32 v32, v4
	v_mov_b32_e32 v33, v4
	v_mov_b32_e32 v34, v4
	v_mov_b32_e32 v35, v4
	v_mov_b32_e32 v36, v4
	v_mov_b32_e32 v37, v4
	v_mov_b32_e32 v38, v4
	v_mov_b32_e32 v39, v4
	v_mov_b32_e32 v40, v4
	v_mov_b32_e32 v41, v4
	v_mov_b32_e32 v42, v4
	v_mov_b32_e32 v43, v4
	v_mov_b32_e32 v44, v4
	v_mov_b32_e32 v45, v4
	v_mov_b32_e32 v46, v4
	v_mov_b32_e32 v47, v4
	v_mov_b32_e32 v48, v4
	v_mov_b32_e32 v49, v4
	v_mov_b32_e32 v50, v4
	v_mov_b32_e32 v51, v4
	v_mov_b32_e32 v52, v4
	v_mov_b32_e32 v53, v4
	v_mov_b32_e32 v54, v4
	v_mov_b32_e32 v55, v4
	v_mov_b32_e32 v56, v4
	v_mov_b32_e32 v57, v4
	v_mov_b32_e32 v58, v4
	v_mov_b32_e32 v59, v4
	v_mov_b32_e32 v60, v4
	v_mov_b32_e32 v61, v4
	v_mov_b32_e32 v62, v4
	v_mov_b32_e32 v63, v4
	v_mov_b32_e32 v64, v4
	v_mov_b32_e32 v65, v4
	v_mov_b32_e32 v66, v4
	v_mov_b32_e32 v67, v4
	v_mov_b32_e32 v68, v4
	v_mov_b32_e32 v69, v4
	v_mov_b32_e32 v70, v4
	v_mov_b32_e32 v71, v4
	v_mov_b32_e32 v72, v4
	v_mov_b32_e32 v73, v4
	v_mov_b32_e32 v74, v4
	v_mov_b32_e32 v75, v4
	v_mov_b32_e32 v76, v4
	v_mov_b32_e32 v77, v4
	v_mov_b32_e32 v78, v4
	v_mov_b32_e32 v79, v4
	v_mov_b32_e32 v80, v4
	v_mov_b32_e32 v81, v4
	v_mov_b32_e32 v82, v4
	v_mov_b32_e32 v83, v4
	v_mov_b32_e32 v84, v4
	v_mov_b32_e32 v85, v4
	v_mov_b32_e32 v86, v4
	v_mov_b32_e32 v87, v4
	v_mov_b32_e32 v88, v4
	v_mov_b32_e32 v89, v4
	v_mov_b32_e32 v90, v4
	v_mov_b32_e32 v91, v4
	v_mov_b32_e32 v92, v4
	v_mov_b32_e32 v93, v4
	v_mov_b32_e32 v94, v4
	v_mov_b32_e32 v95, v4
	v_mov_b32_e32 v96, v4
	v_mov_b32_e32 v97, v4
	v_mov_b32_e32 v98, v4
	v_mov_b32_e32 v99, v4
	v_mov_b32_e32 v100, v4
	v_mov_b32_e32 v101, v4
	v_mov_b32_e32 v102, v4
	v_mov_b32_e32 v103, v4
	v_mov_b32_e32 v104, v4
	v_mov_b32_e32 v105, v4
	v_mov_b32_e32 v106, v4
	v_mov_b32_e32 v107, v4
	v_mov_b32_e32 v108, v4
	v_mov_b32_e32 v109, v4
	v_mov_b32_e32 v110, v4
	v_mov_b32_e32 v111, v4
	v_mov_b32_e32 v112, v4
	v_mov_b32_e32 v113, v4
	v_mov_b32_e32 v114, v4
	v_mov_b32_e32 v115, v4
	v_mov_b32_e32 v116, v4
	v_mov_b32_e32 v117, v4
	v_mov_b32_e32 v118, v4
	v_mov_b32_e32 v119, v4
	v_mov_b32_e32 v120, v4
	v_mov_b32_e32 v121, v4
	v_mov_b32_e32 v122, v4
	v_mov_b32_e32 v123, v4
	v_mov_b32_e32 v124, v4
	v_mov_b32_e32 v125, v4
	v_mov_b32_e32 v126, v4
	v_mov_b32_e32 v127, v4
	v_mov_b32_e32 v128, v4
	v_mov_b32_e32 v129, v4
	v_mov_b32_e32 v130, v4
	v_mov_b32_e32 v131, v4
	s_branch .LBB0_621
